# EpiResid main epilogue: residual loads issued 4 row-blocks ahead of use (measured properly this time)
# speedup vs baseline: 1.0161x; 1.0161x over previous
; __device__ __forceinline__ unsigned cvt_pk_bf16(float lo, float hi) { const f32x2 v = {lo, hi}; return __builtin_bit_cast(unsigned, __builtin_convertvector(v, bf16x2_t)); }
; __device__ __forceinline__ float dot4(f32x4 v) { return (v.x * v.x + v.y * v.y) + (v.z * v.z + v.w * v.w); }
; __device__ __forceinline__ float quad_sum(float t, int lane) { t += shx(t, 16, lane); t += shx(t, 32, lane); return t; }
;     template <int A0, int A1> __device__ __forceinline__ void run(const f32x4 (&acc)[2][2][4][2], const Unit& u, int wr, int wc, int fr, int fq) const {
;         const int s = stream_of(u.pm);
;         const float gmul = full_gate ? 1.0f : 0.5f;
;         const float* xo = (u.pm < 64) ? xo_lat : xo_ctx - (size_t)ML * DM;
;         float* xn = (u.pm < 64) ? xn_lat : xn_ctx - (size_t)ML * DM;
;         const int row0 = u.pm * 256 + wr * 64 + fr;
;         float ssq[2][4];
; #pragma unroll
;         for (int ai = A0; ai < A1; ++ai)
; #pragma unroll
;             for (int m = 0; m < 4; ++m) ssq[ai][m] = 0.f;
; #pragma unroll
;         for (int bj = 0; bj < 2; ++bj) {
;             const int col = u.pn * 256 + bj * 128 + wc * 32 + fq * 8;
;             const f32x4 gv0 = *(const f32x4*)(gate + s * NMOD + col) * gmul, gv1 = *(const f32x4*)(gate + s * NMOD + col + 4) * gmul;
;             f32x4 wv0 = (f32x4){0.f, 0.f, 0.f, 0.f}, wv1 = wv0;
;             if (has_next) { wv0 = *(const f32x4*)(nw + col) * (*(const f32x4*)(nscale + s * NMOD + col) + 1.0f); wv1 = *(const f32x4*)(nw + col + 4) * (*(const f32x4*)(nscale + s * NMOD + col + 4) + 1.0f); }
;     ...
;                     ssq[ai][m] += dot4(x0) + dot4(x1);
;                     if (has_next) { const f32x4 y0 = x0 * wv0, y1 = x1 * wv1; u32x4 w; w.x = cvt_pk_bf16(y0.x, y0.y); w.y = cvt_pk_bf16(y0.z, y0.w); w.z = cvt_pk_bf16(y1.x, y1.y); w.w = cvt_pk_bf16(y1.z, y1.w); *(u32x4*)(Xw + off) = w; }
;                 }
;         }
; #pragma unroll
;         for (int ai = A0; ai < A1; ++ai)
; #pragma unroll
;             for (int m = 0; m < 4; ++m) {
;                 const float t = quad_sum(ssq[ai][m], fq * 16 + fr);
;                 if (fq == 0) ssqp[(size_t)(row0 + ai * 128 + m * 16) * 16 + u.pn * 4 + wc] = t;
;             }
.LBB0_1237:
	s_cmp_lt_u32 s67, 64
	s_movk_i32 s0, 0x2400
	s_cselect_b32 s8, s0, 0x4800
	s_cmp_gt_i32 s67, 31
	s_cselect_b32 s8, s8, 0
	s_lshl_b32 s20, s8, 2
	v_lshl_or_b32 v184, s63, 8, v242
	s_add_u32 s8, s46, s20
	s_addc_u32 s9, s47, 0
	v_ashrrev_i32_e32 v185, 31, v184
	v_lshl_add_u64 v[220:221], v[184:185], 2, s[8:9]
	global_load_dwordx4 v[130:133], v[220:221], off offset:16
	global_load_dwordx4 v[134:137], v[220:221], off
	v_cndmask_b32_e64 v145, 0, 1, s[74:75]
	v_lshlrev_b64 v[218:219], 2, v[184:185]
	v_mov_b32_e32 v224, 0
	v_cmp_ne_u32_e64 s[8:9], 1, v145
	s_andn2_b64 vcc, exec, s[74:75]
	v_lshl_add_u64 v[214:215], s[16:17], 0, v[218:219]
	v_mov_b32_e32 v225, 0
	v_mov_b32_e32 v226, 0
	v_mov_b32_e32 v227, 0
	v_mov_b32_e32 v228, 0
	v_mov_b32_e32 v229, 0
	v_mov_b32_e32 v230, 0
	v_mov_b32_e32 v231, 0
	s_cbranch_vccnz .LBB0_1239
	s_add_u32 s36, s78, s20
	s_addc_u32 s37, s79, 0
	v_lshl_add_u64 v[156:157], s[36:37], 0, v[218:219]
	global_load_dwordx4 v[152:155], v[156:157], off
	s_nop 0
	global_load_dwordx4 v[156:159], v[156:157], off offset:16
	s_nop 0
	global_load_dwordx4 v[160:163], v[214:215], off
	global_load_dwordx4 v[164:167], v[214:215], off offset:16
	s_waitcnt vmcnt(0)
	v_pk_add_f32 v[154:155], v[154:155], 1.0 op_sel_hi:[1,0]
	v_pk_add_f32 v[152:153], v[152:153], 1.0 op_sel_hi:[1,0]
	v_pk_add_f32 v[158:159], v[158:159], 1.0 op_sel_hi:[1,0]
	v_pk_add_f32 v[156:157], v[156:157], 1.0 op_sel_hi:[1,0]
	v_pk_mul_f32 v[230:231], v[162:163], v[154:155]
	v_pk_mul_f32 v[228:229], v[160:161], v[152:153]
	v_pk_mul_f32 v[226:227], v[166:167], v[158:159]
	v_pk_mul_f32 v[224:225], v[164:165], v[156:157]
.LBB0_1239:
	s_branch .Lep_mid
.LBB0_1273:
	v_mul_f32_e32 v93, v93, v93
	v_mul_f32_e32 v89, v89, v89
	v_mul_f32_e32 v61, v61, v61
	v_mul_f32_e32 v57, v57, v57
	v_fmac_f32_e32 v93, v92, v92
	v_mul_f32_e32 v92, v95, v95
	v_fmac_f32_e32 v89, v88, v88
	v_mul_f32_e32 v88, v91, v91
	v_fmac_f32_e32 v61, v60, v60
	v_mul_f32_e32 v60, v63, v63
	v_fmac_f32_e32 v57, v56, v56
	v_mul_f32_e32 v56, v59, v59
	v_fmac_f32_e32 v92, v94, v94
	v_fmac_f32_e32 v88, v90, v90
	v_fmac_f32_e32 v60, v62, v62
	v_fmac_f32_e32 v56, v58, v58
	v_add_f32_e32 v92, v93, v92
	v_add_f32_e32 v88, v89, v88
	v_add_f32_e32 v60, v61, v60
	v_add_f32_e32 v56, v57, v56
	v_add_f32_e32 v88, v92, v88
	v_add_f32_e32 v56, v60, v56
	v_add_f32_e32 v56, v88, v56
	ds_bpermute_b32 v57, v243, v56
	s_lshl_b32 s8, s63, 2
	s_ashr_i32 s9, s8, 31
	s_lshl_b64 s[8:9], s[8:9], 2
	s_add_u32 s8, s96, s8
	s_waitcnt lgkmcnt(0)
	v_add_f32_e32 v56, v56, v57
	ds_bpermute_b32 v57, v244, v56
	s_addc_u32 s9, s97, s9
	s_and_saveexec_b64 s[20:21], s[4:5]
	s_cbranch_execz .LBB0_1275
	v_lshlrev_b64 v[58:59], 6, v[152:153]
	v_lshl_add_u64 v[58:59], s[8:9], 0, v[58:59]
	s_waitcnt lgkmcnt(0)
	v_add_f32_e32 v56, v56, v57
	global_store_dword v[58:59], v56, off

; __device__ __forceinline__ unsigned cvt_pk_bf16(float lo, float hi) { const f32x2 v = {lo, hi}; return __builtin_bit_cast(unsigned, __builtin_convertvector(v, bf16x2_t)); }
; __device__ __forceinline__ float dot4(f32x4 v) { return (v.x * v.x + v.y * v.y) + (v.z * v.z + v.w * v.w); }
;     template <int A0, int A1> __device__ __forceinline__ void run(const f32x4 (&acc)[2][2][4][2], const Unit& u, int wr, int wc, int fr, int fq) const {
;     ...
;         const float* xo = (u.pm < 64) ? xo_lat : xo_ctx - (size_t)ML * DM;
;         float* xn = (u.pm < 64) ? xn_lat : xn_ctx - (size_t)ML * DM;
;         const int row0 = u.pm * 256 + wr * 64 + fr;
;         float ssq[2][4];
; #pragma unroll
;         for (int ai = A0; ai < A1; ++ai)
; #pragma unroll
;             for (int m = 0; m < 4; ++m) ssq[ai][m] = 0.f;
; #pragma unroll
;         for (int bj = 0; bj < 2; ++bj) {
;             const int col = u.pn * 256 + bj * 128 + wc * 32 + fq * 8;
;             const f32x4 gv0 = *(const f32x4*)(gate + s * NMOD + col) * gmul, gv1 = *(const f32x4*)(gate + s * NMOD + col + 4) * gmul;
;             f32x4 wv0 = (f32x4){0.f, 0.f, 0.f, 0.f}, wv1 = wv0;
;             if (has_next) { wv0 = *(const f32x4*)(nw + col) * (*(const f32x4*)(nscale + s * NMOD + col) + 1.0f); wv1 = *(const f32x4*)(nw + col + 4) * (*(const f32x4*)(nscale + s * NMOD + col + 4) + 1.0f); }
; #pragma unroll
;             for (int ai = A0; ai < A1; ++ai)
; #pragma unroll
;                 for (int m = 0; m < 4; ++m) {
;                     const size_t off = (size_t)(row0 + ai * 128 + m * 16) * DM + col;
;                     const f32x4 x0 = *(const f32x4*)(xo + off) + gv0 * acc[ai][bj][m][0];
;                     const f32x4 x1 = *(const f32x4*)(xo + off + 4) + gv1 * acc[ai][bj][m][1];
;                     *(f32x4*)(xn + off) = x0; *(f32x4*)(xn + off + 4) = x1;
;                     ssq[ai][m] += dot4(x0) + dot4(x1);
;                     if (has_next) { const f32x4 y0 = x0 * wv0, y1 = x1 * wv1; u32x4 w; w.x = cvt_pk_bf16(y0.x, y0.y); w.y = cvt_pk_bf16(y0.z, y0.w); w.z = cvt_pk_bf16(y1.x, y1.y); w.w = cvt_pk_bf16(y1.z, y1.w); *(u32x4*)(Xw + off) = w; }
;                 }
.Lep_mid:
	v_lshl_add_u32 v152, s67, 8, v240
	v_ashrrev_i32_e32 v153, 31, v152
	v_or_b32_e32 v154, 16, v152
	v_ashrrev_i32_e32 v155, 31, v154
	v_or_b32_e32 v156, 32, v152
	v_ashrrev_i32_e32 v157, 31, v156
	v_or_b32_e32 v158, 48, v152
	v_ashrrev_i32_e32 v159, 31, v158
	v_add_u32_e32 v160, 0x80, v152
	v_ashrrev_i32_e32 v161, 31, v160
	v_add_u32_e32 v162, 0x90, v152
	v_ashrrev_i32_e32 v163, 31, v162
	v_add_u32_e32 v164, 0xa0, v152
	v_ashrrev_i32_e32 v165, 31, v164
	v_add_u32_e32 v166, 0xb0, v152
	v_ashrrev_i32_e32 v167, 31, v166
	v_lshlrev_b64 v[202:203], 10, v[152:153]
	s_cmp_lt_i32 s67, 64
	v_lshl_add_u64 v[202:203], v[202:203], 0, v[184:185]
	s_cselect_b32 s37, s29, s84
	s_cselect_b32 s36, s28, s43
	v_lshlrev_b64 v[204:205], 2, v[202:203]
	s_cselect_b32 s39, s83, s71
	s_cselect_b32 s38, s82, s85
	v_lshl_add_u64 v[210:211], s[36:37], 0, v[204:205]
	v_lshl_add_u64 v[212:213], s[38:39], 0, v[204:205]
	v_lshl_add_u64 v[216:217], v[202:203], 1, s[22:23]
	v_mov_b32_e32 v222, 0x10000
	v_mov_b32_e32 v223, 0
	v_mov_b32_e32 v232, 0x50000
	v_mov_b32_e32 v233, 0
	v_mov_b32_e32 v234, 0xfff50000
	v_mov_b32_e32 v235, -1
	v_mov_b32_e32 v236, 0x8000
	v_mov_b32_e32 v237, 0
	v_mov_b32_e32 v246, 0x28000
	v_mov_b32_e32 v247, 0
	v_mov_b32_e32 v248, 0xfffa8000
	v_mov_b32_e32 v249, -1
	global_load_dwordx4 v[168:171], v[210:211], off
	global_load_dwordx4 v[172:175], v[210:211], off offset:16
	v_lshl_add_u64 v[210:211], v[210:211], 0, v[222:223]
	global_load_dwordx4 v[176:179], v[210:211], off
	global_load_dwordx4 v[180:183], v[210:211], off offset:16
	v_lshl_add_u64 v[210:211], v[210:211], 0, v[222:223]
	global_load_dwordx4 v[186:189], v[210:211], off
	global_load_dwordx4 v[190:193], v[210:211], off offset:16
	v_lshl_add_u64 v[210:211], v[210:211], 0, v[222:223]
	global_load_dwordx4 v[194:197], v[210:211], off
	global_load_dwordx4 v[198:201], v[210:211], off offset:16
	v_lshl_add_u64 v[210:211], v[210:211], 0, v[232:233]
	v_mov_b32_e32 v145, v144
	s_waitcnt vmcnt(8)
	v_pk_mul_f32 v[136:137], v[144:145], v[136:137]
	v_pk_mul_f32 v[134:135], v[146:147], v[134:135]
	v_pk_mul_f32 v[132:133], v[144:145], v[132:133]
	v_pk_mul_f32 v[130:131], v[146:147], v[130:131]
	s_waitcnt vmcnt(7)
	v_pk_fma_f32 v[94:95], v[94:95], v[136:137], v[170:171]
	v_pk_fma_f32 v[92:93], v[92:93], v[134:135], v[168:169]
	s_waitcnt vmcnt(6)
	v_pk_fma_f32 v[90:91], v[90:91], v[132:133], v[174:175]
	v_pk_fma_f32 v[88:89], v[88:89], v[130:131], v[172:173]
	s_and_b64 vcc, exec, s[8:9]
	global_store_dwordx4 v[212:213], v[92:95], off
	global_store_dwordx4 v[212:213], v[88:91], off offset:16
	s_cbranch_vccnz .Lep_skip0
	v_pk_mul_f32 v[170:171], v[230:231], v[94:95]
	v_pk_mul_f32 v[168:169], v[228:229], v[92:93]
	v_pk_mul_f32 v[174:175], v[226:227], v[90:91]
	v_pk_mul_f32 v[172:173], v[224:225], v[88:89]
	v_cvt_pk_bf16_f32 v168, v168, v169
	v_cvt_pk_bf16_f32 v169, v170, v171
	v_cvt_pk_bf16_f32 v170, v172, v173
	v_cvt_pk_bf16_f32 v171, v174, v175
	global_store_dwordx4 v[216:217], v[168:171], off
	s_nop 1
.Lep_skip0:
	v_lshl_add_u64 v[212:213], v[212:213], 0, v[222:223]
	v_lshl_add_u64 v[216:217], v[216:217], 0, v[236:237]
	global_load_dwordx4 v[168:171], v[210:211], off
	global_load_dwordx4 v[172:175], v[210:211], off offset:16
	v_lshl_add_u64 v[210:211], v[210:211], 0, v[222:223]
	s_waitcnt vmcnt(9)
	v_pk_fma_f32 v[110:111], v[110:111], v[136:137], v[178:179]
	v_pk_fma_f32 v[108:109], v[108:109], v[134:135], v[176:177]
	s_waitcnt vmcnt(8)
	v_pk_fma_f32 v[102:103], v[102:103], v[132:133], v[182:183]
	v_pk_fma_f32 v[100:101], v[100:101], v[130:131], v[180:181]
	s_and_b64 vcc, exec, s[8:9]
	global_store_dwordx4 v[212:213], v[108:111], off
	global_store_dwordx4 v[212:213], v[100:103], off offset:16
	s_cbranch_vccnz .Lep_skip1
	v_pk_mul_f32 v[178:179], v[230:231], v[110:111]
	v_pk_mul_f32 v[176:177], v[228:229], v[108:109]
	v_pk_mul_f32 v[182:183], v[226:227], v[102:103]
	v_pk_mul_f32 v[180:181], v[224:225], v[100:101]
	v_cvt_pk_bf16_f32 v176, v176, v177
	v_cvt_pk_bf16_f32 v177, v178, v179
	v_cvt_pk_bf16_f32 v178, v180, v181
	v_cvt_pk_bf16_f32 v179, v182, v183
	global_store_dwordx4 v[216:217], v[176:179], off
	s_nop 1
.Lep_skip1:
	v_lshl_add_u64 v[212:213], v[212:213], 0, v[222:223]
	v_lshl_add_u64 v[216:217], v[216:217], 0, v[236:237]
	global_load_dwordx4 v[176:179], v[210:211], off
	global_load_dwordx4 v[180:183], v[210:211], off offset:16
	v_lshl_add_u64 v[210:211], v[210:211], 0, v[222:223]
	s_waitcnt vmcnt(11)
	v_pk_fma_f32 v[118:119], v[118:119], v[136:137], v[188:189]
	v_pk_fma_f32 v[116:117], v[116:117], v[134:135], v[186:187]
	s_waitcnt vmcnt(10)
	v_pk_fma_f32 v[114:115], v[114:115], v[132:133], v[192:193]
	v_pk_fma_f32 v[112:113], v[112:113], v[130:131], v[190:191]
	s_and_b64 vcc, exec, s[8:9]
	global_store_dwordx4 v[212:213], v[116:119], off
	global_store_dwordx4 v[212:213], v[112:115], off offset:16
	s_cbranch_vccnz .Lep_skip2
	v_pk_mul_f32 v[188:189], v[230:231], v[118:119]
	v_pk_mul_f32 v[186:187], v[228:229], v[116:117]
	v_pk_mul_f32 v[192:193], v[226:227], v[114:115]
	v_pk_mul_f32 v[190:191], v[224:225], v[112:113]
	v_cvt_pk_bf16_f32 v186, v186, v187
	v_cvt_pk_bf16_f32 v187, v188, v189
	v_cvt_pk_bf16_f32 v188, v190, v191
	v_cvt_pk_bf16_f32 v189, v192, v193
	global_store_dwordx4 v[216:217], v[186:189], off
	s_nop 1
; __device__ __forceinline__ unsigned cvt_pk_bf16(float lo, float hi) { const f32x2 v = {lo, hi}; return __builtin_bit_cast(unsigned, __builtin_convertvector(v, bf16x2_t)); }
; __device__ __forceinline__ float dot4(f32x4 v) { return (v.x * v.x + v.y * v.y) + (v.z * v.z + v.w * v.w); }
;     template <int A0, int A1> __device__ __forceinline__ void run(const f32x4 (&acc)[2][2][4][2], const Unit& u, int wr, int wc, int fr, int fq) const {
;     ...
; #pragma unroll
;             for (int ai = A0; ai < A1; ++ai)
; #pragma unroll
;                 for (int m = 0; m < 4; ++m) {
;                     const size_t off = (size_t)(row0 + ai * 128 + m * 16) * DM + col;
;                     const f32x4 x0 = *(const f32x4*)(xo + off) + gv0 * acc[ai][bj][m][0];
;                     const f32x4 x1 = *(const f32x4*)(xo + off + 4) + gv1 * acc[ai][bj][m][1];
;                     *(f32x4*)(xn + off) = x0; *(f32x4*)(xn + off + 4) = x1;
;                     ssq[ai][m] += dot4(x0) + dot4(x1);
;                     if (has_next) { const f32x4 y0 = x0 * wv0, y1 = x1 * wv1; u32x4 w; w.x = cvt_pk_bf16(y0.x, y0.y); w.y = cvt_pk_bf16(y0.z, y0.w); w.z = cvt_pk_bf16(y1.x, y1.y); w.w = cvt_pk_bf16(y1.z, y1.w); *(u32x4*)(Xw + off) = w; }
;                 }
.Lep_skip2:
	v_lshl_add_u64 v[212:213], v[212:213], 0, v[222:223]
	v_lshl_add_u64 v[216:217], v[216:217], 0, v[236:237]
	global_load_dwordx4 v[186:189], v[210:211], off
	global_load_dwordx4 v[190:193], v[210:211], off offset:16
	v_lshl_add_u64 v[210:211], v[210:211], 0, v[222:223]
	s_waitcnt vmcnt(13)
	v_pk_fma_f32 v[126:127], v[126:127], v[136:137], v[196:197]
	v_pk_fma_f32 v[124:125], v[124:125], v[134:135], v[194:195]
	s_waitcnt vmcnt(12)
	v_pk_fma_f32 v[122:123], v[122:123], v[132:133], v[200:201]
	v_pk_fma_f32 v[120:121], v[120:121], v[130:131], v[198:199]
	s_and_b64 vcc, exec, s[8:9]
	global_store_dwordx4 v[212:213], v[124:127], off
	global_store_dwordx4 v[212:213], v[120:123], off offset:16
	s_cbranch_vccnz .Lep_skip3
	v_pk_mul_f32 v[196:197], v[230:231], v[126:127]
	v_pk_mul_f32 v[194:195], v[228:229], v[124:125]
	v_pk_mul_f32 v[200:201], v[226:227], v[122:123]
	v_pk_mul_f32 v[198:199], v[224:225], v[120:121]
	v_cvt_pk_bf16_f32 v194, v194, v195
	v_cvt_pk_bf16_f32 v195, v196, v197
	v_cvt_pk_bf16_f32 v196, v198, v199
	v_cvt_pk_bf16_f32 v197, v200, v201
	global_store_dwordx4 v[216:217], v[194:197], off
	s_nop 1
.Lep_skip3:
	v_lshl_add_u64 v[212:213], v[212:213], 0, v[232:233]
	v_lshl_add_u64 v[216:217], v[216:217], 0, v[246:247]
	global_load_dwordx4 v[194:197], v[210:211], off
	global_load_dwordx4 v[198:201], v[210:211], off offset:16
	v_lshl_add_u64 v[210:211], v[210:211], 0, v[234:235]
	s_waitcnt vmcnt(13)
	v_pk_fma_f32 v[106:107], v[106:107], v[136:137], v[170:171]
	v_pk_fma_f32 v[104:105], v[104:105], v[134:135], v[168:169]
	s_waitcnt vmcnt(12)
	v_pk_fma_f32 v[98:99], v[98:99], v[132:133], v[174:175]
	v_pk_fma_f32 v[96:97], v[96:97], v[130:131], v[172:173]
	s_and_b64 vcc, exec, s[8:9]
	global_store_dwordx4 v[212:213], v[104:107], off
	global_store_dwordx4 v[212:213], v[96:99], off offset:16
	s_cbranch_vccnz .Lep_skip4
	v_pk_mul_f32 v[170:171], v[230:231], v[106:107]
	v_pk_mul_f32 v[168:169], v[228:229], v[104:105]
	v_pk_mul_f32 v[174:175], v[226:227], v[98:99]
	v_pk_mul_f32 v[172:173], v[224:225], v[96:97]
	v_cvt_pk_bf16_f32 v168, v168, v169
	v_cvt_pk_bf16_f32 v169, v170, v171
	v_cvt_pk_bf16_f32 v170, v172, v173
	v_cvt_pk_bf16_f32 v171, v174, v175
	global_store_dwordx4 v[216:217], v[168:171], off
	s_nop 1
.Lep_skip4:
	v_lshl_add_u64 v[212:213], v[212:213], 0, v[222:223]
	v_lshl_add_u64 v[216:217], v[216:217], 0, v[236:237]
	global_load_dwordx4 v[168:171], v[210:211], off offset:512
	global_load_dwordx4 v[172:175], v[210:211], off offset:528
	v_lshl_add_u64 v[210:211], v[210:211], 0, v[222:223]
	s_waitcnt vmcnt(13)
	v_pk_fma_f32 v[86:87], v[86:87], v[136:137], v[178:179]
	v_pk_fma_f32 v[84:85], v[84:85], v[134:135], v[176:177]
	s_waitcnt vmcnt(12)
	v_pk_fma_f32 v[82:83], v[82:83], v[132:133], v[182:183]
	v_pk_fma_f32 v[80:81], v[80:81], v[130:131], v[180:181]
	s_and_b64 vcc, exec, s[8:9]
	global_store_dwordx4 v[212:213], v[84:87], off
	global_store_dwordx4 v[212:213], v[80:83], off offset:16
	s_cbranch_vccnz .Lep_skip5
	v_pk_mul_f32 v[178:179], v[230:231], v[86:87]
	v_pk_mul_f32 v[176:177], v[228:229], v[84:85]
	v_pk_mul_f32 v[182:183], v[226:227], v[82:83]
	v_pk_mul_f32 v[180:181], v[224:225], v[80:81]
	v_cvt_pk_bf16_f32 v176, v176, v177
	v_cvt_pk_bf16_f32 v177, v178, v179
	v_cvt_pk_bf16_f32 v178, v180, v181
	v_cvt_pk_bf16_f32 v179, v182, v183
	global_store_dwordx4 v[216:217], v[176:179], off
	s_nop 1
.Lep_skip5:
	v_lshl_add_u64 v[212:213], v[212:213], 0, v[222:223]
	v_lshl_add_u64 v[216:217], v[216:217], 0, v[236:237]
	global_load_dwordx4 v[176:179], v[210:211], off offset:512
	global_load_dwordx4 v[180:183], v[210:211], off offset:528
	v_lshl_add_u64 v[210:211], v[210:211], 0, v[222:223]
	s_waitcnt vmcnt(13)
	v_pk_fma_f32 v[78:79], v[78:79], v[136:137], v[188:189]
	v_pk_fma_f32 v[76:77], v[76:77], v[134:135], v[186:187]
	s_waitcnt vmcnt(12)
	v_pk_fma_f32 v[74:75], v[74:75], v[132:133], v[192:193]
	v_pk_fma_f32 v[72:73], v[72:73], v[130:131], v[190:191]
	s_and_b64 vcc, exec, s[8:9]
	global_store_dwordx4 v[212:213], v[76:79], off
	global_store_dwordx4 v[212:213], v[72:75], off offset:16
	s_cbranch_vccnz .Lep_skip6
	v_pk_mul_f32 v[188:189], v[230:231], v[78:79]
	v_pk_mul_f32 v[186:187], v[228:229], v[76:77]
	v_pk_mul_f32 v[192:193], v[226:227], v[74:75]
	v_pk_mul_f32 v[190:191], v[224:225], v[72:73]
	v_cvt_pk_bf16_f32 v186, v186, v187
	v_cvt_pk_bf16_f32 v187, v188, v189
	v_cvt_pk_bf16_f32 v188, v190, v191
	v_cvt_pk_bf16_f32 v189, v192, v193
	global_store_dwordx4 v[216:217], v[186:189], off
	s_nop 1
.Lep_skip6:
	v_lshl_add_u64 v[212:213], v[212:213], 0, v[222:223]
	v_lshl_add_u64 v[216:217], v[216:217], 0, v[236:237]
	global_load_dwordx4 v[186:189], v[210:211], off offset:512
	global_load_dwordx4 v[190:193], v[210:211], off offset:528
	v_lshl_add_u64 v[210:211], v[210:211], 0, v[222:223]
	s_waitcnt vmcnt(13)
	v_pk_fma_f32 v[70:71], v[70:71], v[136:137], v[196:197]
	v_pk_fma_f32 v[68:69], v[68:69], v[134:135], v[194:195]
	s_waitcnt vmcnt(12)
	v_pk_fma_f32 v[66:67], v[66:67], v[132:133], v[200:201]
	v_pk_fma_f32 v[64:65], v[64:65], v[130:131], v[198:199]
	s_and_b64 vcc, exec, s[8:9]
	global_store_dwordx4 v[212:213], v[68:71], off
	global_store_dwordx4 v[212:213], v[64:67], off offset:16
	s_cbranch_vccnz .Lep_skip7
	v_pk_mul_f32 v[196:197], v[230:231], v[70:71]
	v_pk_mul_f32 v[194:195], v[228:229], v[68:69]
	v_pk_mul_f32 v[200:201], v[226:227], v[66:67]
	v_pk_mul_f32 v[198:199], v[224:225], v[64:65]
	v_cvt_pk_bf16_f32 v194, v194, v195
	v_cvt_pk_bf16_f32 v195, v196, v197
	v_cvt_pk_bf16_f32 v196, v198, v199
	v_cvt_pk_bf16_f32 v197, v200, v201
	global_store_dwordx4 v[216:217], v[194:197], off
	s_nop 1
; __device__ __forceinline__ unsigned cvt_pk_bf16(float lo, float hi) { const f32x2 v = {lo, hi}; return __builtin_bit_cast(unsigned, __builtin_convertvector(v, bf16x2_t)); }
; __device__ __forceinline__ float dot4(f32x4 v) { return (v.x * v.x + v.y * v.y) + (v.z * v.z + v.w * v.w); }
;     template <int A0, int A1> __device__ __forceinline__ void run(const f32x4 (&acc)[2][2][4][2], const Unit& u, int wr, int wc, int fr, int fq) const {
;     ...
;         for (int bj = 0; bj < 2; ++bj) {
;             const int col = u.pn * 256 + bj * 128 + wc * 32 + fq * 8;
;             const f32x4 gv0 = *(const f32x4*)(gate + s * NMOD + col) * gmul, gv1 = *(const f32x4*)(gate + s * NMOD + col + 4) * gmul;
;             f32x4 wv0 = (f32x4){0.f, 0.f, 0.f, 0.f}, wv1 = wv0;
;             if (has_next) { wv0 = *(const f32x4*)(nw + col) * (*(const f32x4*)(nscale + s * NMOD + col) + 1.0f); wv1 = *(const f32x4*)(nw + col + 4) * (*(const f32x4*)(nscale + s * NMOD + col + 4) + 1.0f); }
; #pragma unroll
;             for (int ai = A0; ai < A1; ++ai)
; #pragma unroll
;                 for (int m = 0; m < 4; ++m) {
;                     const size_t off = (size_t)(row0 + ai * 128 + m * 16) * DM + col;
;                     const f32x4 x0 = *(const f32x4*)(xo + off) + gv0 * acc[ai][bj][m][0];
;                     const f32x4 x1 = *(const f32x4*)(xo + off + 4) + gv1 * acc[ai][bj][m][1];
;                     *(f32x4*)(xn + off) = x0; *(f32x4*)(xn + off + 4) = x1;
;                     ssq[ai][m] += dot4(x0) + dot4(x1);
;                     if (has_next) { const f32x4 y0 = x0 * wv0, y1 = x1 * wv1; u32x4 w; w.x = cvt_pk_bf16(y0.x, y0.y); w.y = cvt_pk_bf16(y0.z, y0.w); w.z = cvt_pk_bf16(y1.x, y1.y); w.w = cvt_pk_bf16(y1.z, y1.w); *(u32x4*)(Xw + off) = w; }
;                 }
.Lep_skip7:
	v_lshl_add_u64 v[212:213], v[212:213], 0, v[234:235]
	v_lshl_add_u64 v[216:217], v[216:217], 0, v[248:249]
	global_load_dwordx4 v[194:197], v[210:211], off offset:512
	global_load_dwordx4 v[198:201], v[210:211], off offset:528
	v_lshl_add_u64 v[210:211], v[210:211], 0, v[232:233]
	global_load_dwordx4 v[130:133], v[220:221], off offset:528
	global_load_dwordx4 v[134:137], v[220:221], off offset:512
	s_and_b64 vcc, exec, s[8:9]
	s_cbranch_vccnz .Lep_nonext
	s_add_u32 s20, s78, s20
	s_addc_u32 s21, s79, 0
	v_lshl_add_u64 v[206:207], s[20:21], 0, v[218:219]
	global_load_dwordx4 v[228:231], v[206:207], off offset:512
	global_load_dwordx4 v[224:227], v[206:207], off offset:528
	global_load_dwordx4 v[202:205], v[214:215], off offset:512
	global_load_dwordx4 v[206:209], v[214:215], off offset:528
	s_waitcnt vmcnt(0)
	v_pk_add_f32 v[230:231], v[230:231], 1.0 op_sel_hi:[1,0]
	v_pk_add_f32 v[228:229], v[228:229], 1.0 op_sel_hi:[1,0]
	v_pk_add_f32 v[226:227], v[226:227], 1.0 op_sel_hi:[1,0]
	v_pk_add_f32 v[224:225], v[224:225], 1.0 op_sel_hi:[1,0]
	v_pk_mul_f32 v[230:231], v[204:205], v[230:231]
	v_pk_mul_f32 v[228:229], v[202:203], v[228:229]
	v_pk_mul_f32 v[226:227], v[208:209], v[226:227]
	v_pk_mul_f32 v[224:225], v[206:207], v[224:225]
.Lep_nonext:
	s_waitcnt vmcnt(0)
	v_pk_mul_f32 v[136:137], v[144:145], v[136:137]
	v_pk_mul_f32 v[134:135], v[146:147], v[134:135]
	v_pk_mul_f32 v[132:133], v[144:145], v[132:133]
	v_pk_mul_f32 v[130:131], v[146:147], v[130:131]
	s_waitcnt vmcnt(13)
	v_pk_fma_f32 v[62:63], v[62:63], v[136:137], v[170:171]
	v_pk_fma_f32 v[60:61], v[60:61], v[134:135], v[168:169]
	s_waitcnt vmcnt(12)
	v_pk_fma_f32 v[58:59], v[58:59], v[132:133], v[174:175]
	v_pk_fma_f32 v[56:57], v[56:57], v[130:131], v[172:173]
	s_and_b64 vcc, exec, s[8:9]
	global_store_dwordx4 v[212:213], v[60:63], off offset:512
	global_store_dwordx4 v[212:213], v[56:59], off offset:528
	s_cbranch_vccnz .Lep_skip8
	v_pk_mul_f32 v[170:171], v[230:231], v[62:63]
	v_pk_mul_f32 v[168:169], v[228:229], v[60:61]
	v_pk_mul_f32 v[174:175], v[226:227], v[58:59]
	v_pk_mul_f32 v[172:173], v[224:225], v[56:57]
	v_cvt_pk_bf16_f32 v168, v168, v169
	v_cvt_pk_bf16_f32 v169, v170, v171
	v_cvt_pk_bf16_f32 v170, v172, v173
	v_cvt_pk_bf16_f32 v171, v174, v175
	global_store_dwordx4 v[216:217], v[168:171], off offset:256
	s_nop 1
.Lep_skip8:
	v_lshl_add_u64 v[212:213], v[212:213], 0, v[222:223]
	v_lshl_add_u64 v[216:217], v[216:217], 0, v[236:237]
	global_load_dwordx4 v[168:171], v[210:211], off offset:512
	global_load_dwordx4 v[172:175], v[210:211], off offset:528
	v_lshl_add_u64 v[210:211], v[210:211], 0, v[222:223]
	s_waitcnt vmcnt(13)
	v_pk_fma_f32 v[54:55], v[54:55], v[136:137], v[178:179]
	v_pk_fma_f32 v[52:53], v[52:53], v[134:135], v[176:177]
	s_waitcnt vmcnt(12)
	v_pk_fma_f32 v[50:51], v[50:51], v[132:133], v[182:183]
	v_pk_fma_f32 v[48:49], v[48:49], v[130:131], v[180:181]
	s_and_b64 vcc, exec, s[8:9]
	global_store_dwordx4 v[212:213], v[52:55], off offset:512
	global_store_dwordx4 v[212:213], v[48:51], off offset:528
	s_cbranch_vccnz .Lep_skip9
	v_pk_mul_f32 v[178:179], v[230:231], v[54:55]
	v_pk_mul_f32 v[176:177], v[228:229], v[52:53]
	v_pk_mul_f32 v[182:183], v[226:227], v[50:51]
	v_pk_mul_f32 v[180:181], v[224:225], v[48:49]
	v_cvt_pk_bf16_f32 v176, v176, v177
	v_cvt_pk_bf16_f32 v177, v178, v179
	v_cvt_pk_bf16_f32 v178, v180, v181
	v_cvt_pk_bf16_f32 v179, v182, v183
	global_store_dwordx4 v[216:217], v[176:179], off offset:256
	s_nop 1
.Lep_skip9:
	v_lshl_add_u64 v[212:213], v[212:213], 0, v[222:223]
	v_lshl_add_u64 v[216:217], v[216:217], 0, v[236:237]
	global_load_dwordx4 v[176:179], v[210:211], off offset:512
	global_load_dwordx4 v[180:183], v[210:211], off offset:528
	v_lshl_add_u64 v[210:211], v[210:211], 0, v[222:223]
	s_waitcnt vmcnt(13)
	v_pk_fma_f32 v[46:47], v[46:47], v[136:137], v[188:189]
	v_pk_fma_f32 v[44:45], v[44:45], v[134:135], v[186:187]
	s_waitcnt vmcnt(12)
	v_pk_fma_f32 v[42:43], v[42:43], v[132:133], v[192:193]
	v_pk_fma_f32 v[40:41], v[40:41], v[130:131], v[190:191]
	s_and_b64 vcc, exec, s[8:9]
	global_store_dwordx4 v[212:213], v[44:47], off offset:512
	global_store_dwordx4 v[212:213], v[40:43], off offset:528
	s_cbranch_vccnz .Lep_skip10
	v_pk_mul_f32 v[188:189], v[230:231], v[46:47]
	v_pk_mul_f32 v[186:187], v[228:229], v[44:45]
	v_pk_mul_f32 v[192:193], v[226:227], v[42:43]
	v_pk_mul_f32 v[190:191], v[224:225], v[40:41]
	v_cvt_pk_bf16_f32 v186, v186, v187
	v_cvt_pk_bf16_f32 v187, v188, v189
	v_cvt_pk_bf16_f32 v188, v190, v191
	v_cvt_pk_bf16_f32 v189, v192, v193
	global_store_dwordx4 v[216:217], v[186:189], off offset:256
	s_nop 1
; __device__ __forceinline__ unsigned cvt_pk_bf16(float lo, float hi) { const f32x2 v = {lo, hi}; return __builtin_bit_cast(unsigned, __builtin_convertvector(v, bf16x2_t)); }
; __device__ __forceinline__ float dot4(f32x4 v) { return (v.x * v.x + v.y * v.y) + (v.z * v.z + v.w * v.w); }
;     template <int A0, int A1> __device__ __forceinline__ void run(const f32x4 (&acc)[2][2][4][2], const Unit& u, int wr, int wc, int fr, int fq) const {
;     ...
; #pragma unroll
;             for (int ai = A0; ai < A1; ++ai)
; #pragma unroll
;                 for (int m = 0; m < 4; ++m) {
;                     const size_t off = (size_t)(row0 + ai * 128 + m * 16) * DM + col;
;                     const f32x4 x0 = *(const f32x4*)(xo + off) + gv0 * acc[ai][bj][m][0];
;                     const f32x4 x1 = *(const f32x4*)(xo + off + 4) + gv1 * acc[ai][bj][m][1];
;                     *(f32x4*)(xn + off) = x0; *(f32x4*)(xn + off + 4) = x1;
;                     ssq[ai][m] += dot4(x0) + dot4(x1);
;                     if (has_next) { const f32x4 y0 = x0 * wv0, y1 = x1 * wv1; u32x4 w; w.x = cvt_pk_bf16(y0.x, y0.y); w.y = cvt_pk_bf16(y0.z, y0.w); w.z = cvt_pk_bf16(y1.x, y1.y); w.w = cvt_pk_bf16(y1.z, y1.w); *(u32x4*)(Xw + off) = w; }
;                 }
.Lep_skip10:
	v_lshl_add_u64 v[212:213], v[212:213], 0, v[222:223]
	v_lshl_add_u64 v[216:217], v[216:217], 0, v[236:237]
	global_load_dwordx4 v[186:189], v[210:211], off offset:512
	global_load_dwordx4 v[190:193], v[210:211], off offset:528
	v_lshl_add_u64 v[210:211], v[210:211], 0, v[222:223]
	s_waitcnt vmcnt(13)
	v_pk_fma_f32 v[38:39], v[38:39], v[136:137], v[196:197]
	v_pk_fma_f32 v[36:37], v[36:37], v[134:135], v[194:195]
	s_waitcnt vmcnt(12)
	v_pk_fma_f32 v[34:35], v[34:35], v[132:133], v[200:201]
	v_pk_fma_f32 v[32:33], v[32:33], v[130:131], v[198:199]
	s_and_b64 vcc, exec, s[8:9]
	global_store_dwordx4 v[212:213], v[36:39], off offset:512
	global_store_dwordx4 v[212:213], v[32:35], off offset:528
	s_cbranch_vccnz .Lep_skip11
	v_pk_mul_f32 v[196:197], v[230:231], v[38:39]
	v_pk_mul_f32 v[194:195], v[228:229], v[36:37]
	v_pk_mul_f32 v[200:201], v[226:227], v[34:35]
	v_pk_mul_f32 v[198:199], v[224:225], v[32:33]
	v_cvt_pk_bf16_f32 v194, v194, v195
	v_cvt_pk_bf16_f32 v195, v196, v197
	v_cvt_pk_bf16_f32 v196, v198, v199
	v_cvt_pk_bf16_f32 v197, v200, v201
	global_store_dwordx4 v[216:217], v[194:197], off offset:256
	s_nop 1
.Lep_skip11:
	v_lshl_add_u64 v[212:213], v[212:213], 0, v[232:233]
	v_lshl_add_u64 v[216:217], v[216:217], 0, v[246:247]
	global_load_dwordx4 v[194:197], v[210:211], off offset:512
	global_load_dwordx4 v[198:201], v[210:211], off offset:528
	s_waitcnt vmcnt(13)
	v_pk_fma_f32 v[30:31], v[30:31], v[136:137], v[170:171]
	v_pk_fma_f32 v[28:29], v[28:29], v[134:135], v[168:169]
	s_waitcnt vmcnt(12)
	v_pk_fma_f32 v[26:27], v[26:27], v[132:133], v[174:175]
	v_pk_fma_f32 v[24:25], v[24:25], v[130:131], v[172:173]
	s_and_b64 vcc, exec, s[8:9]
	global_store_dwordx4 v[212:213], v[28:31], off offset:512
	global_store_dwordx4 v[212:213], v[24:27], off offset:528
	s_cbranch_vccnz .Lep_skip12
	v_pk_mul_f32 v[170:171], v[230:231], v[30:31]
	v_pk_mul_f32 v[168:169], v[228:229], v[28:29]
	v_pk_mul_f32 v[174:175], v[226:227], v[26:27]
	v_pk_mul_f32 v[172:173], v[224:225], v[24:25]
	v_cvt_pk_bf16_f32 v168, v168, v169
	v_cvt_pk_bf16_f32 v169, v170, v171
	v_cvt_pk_bf16_f32 v170, v172, v173
	v_cvt_pk_bf16_f32 v171, v174, v175
	global_store_dwordx4 v[216:217], v[168:171], off offset:256
	s_nop 1
.Lep_skip12:
	v_lshl_add_u64 v[212:213], v[212:213], 0, v[222:223]
	v_lshl_add_u64 v[216:217], v[216:217], 0, v[236:237]
	s_waitcnt vmcnt(11)
	v_pk_fma_f32 v[22:23], v[22:23], v[136:137], v[178:179]
	v_pk_fma_f32 v[20:21], v[20:21], v[134:135], v[176:177]
	s_waitcnt vmcnt(10)
	v_pk_fma_f32 v[18:19], v[18:19], v[132:133], v[182:183]
	v_pk_fma_f32 v[16:17], v[16:17], v[130:131], v[180:181]
	s_and_b64 vcc, exec, s[8:9]
	global_store_dwordx4 v[212:213], v[20:23], off offset:512
	global_store_dwordx4 v[212:213], v[16:19], off offset:528
	s_cbranch_vccnz .Lep_skip13
	v_pk_mul_f32 v[178:179], v[230:231], v[22:23]
	v_pk_mul_f32 v[176:177], v[228:229], v[20:21]
	v_pk_mul_f32 v[182:183], v[226:227], v[18:19]
	v_pk_mul_f32 v[180:181], v[224:225], v[16:17]
	v_cvt_pk_bf16_f32 v176, v176, v177
	v_cvt_pk_bf16_f32 v177, v178, v179
	v_cvt_pk_bf16_f32 v178, v180, v181
	v_cvt_pk_bf16_f32 v179, v182, v183
	global_store_dwordx4 v[216:217], v[176:179], off offset:256
	s_nop 1
.Lep_skip13:
	v_lshl_add_u64 v[212:213], v[212:213], 0, v[222:223]
	v_lshl_add_u64 v[216:217], v[216:217], 0, v[236:237]
	s_waitcnt vmcnt(9)
	v_pk_fma_f32 v[14:15], v[14:15], v[136:137], v[188:189]
	v_pk_fma_f32 v[12:13], v[12:13], v[134:135], v[186:187]
	s_waitcnt vmcnt(8)
	v_pk_fma_f32 v[10:11], v[10:11], v[132:133], v[192:193]
	v_pk_fma_f32 v[8:9], v[8:9], v[130:131], v[190:191]
	s_and_b64 vcc, exec, s[8:9]
	global_store_dwordx4 v[212:213], v[12:15], off offset:512
	global_store_dwordx4 v[212:213], v[8:11], off offset:528
	s_cbranch_vccnz .Lep_skip14
	v_pk_mul_f32 v[188:189], v[230:231], v[14:15]
	v_pk_mul_f32 v[186:187], v[228:229], v[12:13]
	v_pk_mul_f32 v[192:193], v[226:227], v[10:11]
	v_pk_mul_f32 v[190:191], v[224:225], v[8:9]
	v_cvt_pk_bf16_f32 v186, v186, v187
	v_cvt_pk_bf16_f32 v187, v188, v189
	v_cvt_pk_bf16_f32 v188, v190, v191
	v_cvt_pk_bf16_f32 v189, v192, v193
	global_store_dwordx4 v[216:217], v[186:189], off offset:256
	s_nop 1
.Lep_skip14:
	v_lshl_add_u64 v[212:213], v[212:213], 0, v[222:223]
	v_lshl_add_u64 v[216:217], v[216:217], 0, v[236:237]
	s_waitcnt vmcnt(7)
	v_pk_fma_f32 v[6:7], v[6:7], v[136:137], v[196:197]
	v_pk_fma_f32 v[4:5], v[4:5], v[134:135], v[194:195]
	s_waitcnt vmcnt(6)
	v_pk_fma_f32 v[2:3], v[2:3], v[132:133], v[200:201]
	v_pk_fma_f32 v[0:1], v[0:1], v[130:131], v[198:199]
	s_and_b64 vcc, exec, s[8:9]
	global_store_dwordx4 v[212:213], v[4:7], off offset:512
	global_store_dwordx4 v[212:213], v[0:3], off offset:528
	s_cbranch_vccnz .Lep_skip15
	v_pk_mul_f32 v[196:197], v[230:231], v[6:7]
	v_pk_mul_f32 v[194:195], v[228:229], v[4:5]
	v_pk_mul_f32 v[200:201], v[226:227], v[2:3]
	v_pk_mul_f32 v[198:199], v[224:225], v[0:1]
	v_cvt_pk_bf16_f32 v194, v194, v195
	v_cvt_pk_bf16_f32 v195, v196, v197
	v_cvt_pk_bf16_f32 v196, v198, v199
	v_cvt_pk_bf16_f32 v197, v200, v201
	global_store_dwordx4 v[216:217], v[194:197], off offset:256
	s_nop 1
.Lep_skip15:
	s_branch .LBB0_1273
	.section	.rodata,"a",@progbits
	.p2align	6, 0x0
